# FFN2 down-projection epilogue: the four gate-vector loads issued together instead of one round trip each
# speedup vs baseline: 1.0008x; 1.0008x over previous
;     __device__ __forceinline__ void operator()(const f32x4 (&acc)[2][2][4][2], const Unit& u, int wr, int wc, int fr, int fq) const {
;     ...
;         const bool lat = u.pm < (N_LAT / BM);
;         const int r5 = lat ? (u.pm >> 5) : 4;
;         const float* g = gate + (size_t)r5 * MODROW;
;         const int rowt = (lat ? u.pm * BM : u.pm * BM - N_LAT) + wr * 64 + fr;
;         const float* bp = lat ? base_lat : base_ctx; float* op = lat ? out_lat : out_ctx;
;         const int col0 = u.pn * BM + wc * 32 + 4 * fq;
;         f32x4 gv[2][2];
; #pragma unroll
;         for (int bj = 0; bj < 2; ++bj)
; #pragma unroll
;             for (int n = 0; n < 2; ++n) gv[bj][n] = *(const f32x4*)(g + col0 + bj * HALF + n * 16) * s;
; #pragma unroll
;         for (int ai = 0; ai < 2; ++ai) {
;             f32x4 b[4][2][2];
; #pragma unroll
;             for (int m = 0; m < 4; ++m) { const size_t off = (size_t)(rowt + ai * HALF + m * 16) * D_MODEL + col0;
; #pragma unroll
;                 for (int bj = 0; bj < 2; ++bj)
; #pragma unroll
;                     for (int n = 0; n < 2; ++n) b[m][bj][n] = *(const f32x4*)(bp + off + bj * HALF + n * 16); }
; #pragma unroll
;             for (int m = 0; m < 4; ++m) { const size_t off = (size_t)(rowt + ai * HALF + m * 16) * D_MODEL + col0;
; #pragma unroll
;                 for (int bj = 0; bj < 2; ++bj)
; #pragma unroll
;                     for (int n = 0; n < 2; ++n) *(f32x4*)(op + off + bj * HALF + n * 16) = b[m][bj][n] + gv[bj][n] * acc[ai][bj][m][n]; }
.LBB0_974:
	s_lshl_b64 s[22:23], s[22:23], 2
	v_lshl_or_b32 v128, s13, 8, v182
	s_add_u32 s22, s45, s22
	v_ashrrev_i32_e32 v129, 31, v128
	s_addc_u32 s23, s46, s23
	v_lshlrev_b64 v[132:133], 2, v[128:129]
	v_lshl_add_u64 v[134:135], s[22:23], 0, v[132:133]
	global_load_dwordx4 v[128:131], v[134:135], off
	global_load_dwordx4 v[136:139], v[134:135], off offset:64
	global_load_dwordx4 v[140:143], v[134:135], off offset:512
	global_load_dwordx4 v[174:177], v[134:135], off offset:576
	s_lshl_b32 s24, s49, 8
	s_add_i32 s25, s24, 0xffff8000
	s_and_b64 s[20:21], s[20:21], exec
	s_cselect_b32 s20, s24, s25
	v_add_u32_e32 v178, s20, v180
	v_ashrrev_i32_e32 v179, 31, v178
	v_lshl_add_u64 v[194:195], s[2:3], 0, v[132:133]
	v_or_b32_e32 v170, 16, v178
	v_ashrrev_i32_e32 v171, 31, v170
	v_lshlrev_b64 v[170:171], 12, v[170:171]
	v_lshl_add_u64 v[204:205], v[194:195], 0, v[170:171]
	v_or_b32_e32 v198, 32, v178
	v_ashrrev_i32_e32 v199, 31, v198
	v_lshlrev_b64 v[198:199], 12, v[198:199]
	v_lshl_add_u64 v[208:209], v[194:195], 0, v[198:199]
	s_mov_b64 s[2:3], 0x90000
	s_waitcnt vmcnt(0)
	v_pk_mul_f32 v[152:153], v[130:131], 0.5 op_sel_hi:[1,0]
	v_pk_mul_f32 v[154:155], v[128:129], 0.5 op_sel_hi:[1,0]
	v_pk_mul_f32 v[156:157], v[138:139], 0.5 op_sel_hi:[1,0]
	v_pk_mul_f32 v[158:159], v[136:137], 0.5 op_sel_hi:[1,0]
	v_pk_mul_f32 v[160:161], v[142:143], 0.5 op_sel_hi:[1,0]
	v_pk_mul_f32 v[162:163], v[140:141], 0.5 op_sel_hi:[1,0]
	v_pk_mul_f32 v[166:167], v[174:175], 0.5 op_sel_hi:[1,0]
	v_lshlrev_b64 v[128:129], 12, v[178:179]
	v_lshl_add_u64 v[168:169], v[194:195], 0, v[128:129]
	v_pk_mul_f32 v[164:165], v[176:177], 0.5 op_sel_hi:[1,0]
	global_load_dwordx4 v[128:131], v[168:169], off
	global_load_dwordx4 v[132:135], v[168:169], off offset:64
	global_load_dwordx4 v[136:139], v[168:169], off offset:512
	global_load_dwordx4 v[140:143], v[168:169], off offset:576
	global_load_dwordx4 v[170:173], v[204:205], off
	global_load_dwordx4 v[174:177], v[204:205], off offset:64
	global_load_dwordx4 v[184:187], v[204:205], off offset:512
	global_load_dwordx4 v[188:191], v[204:205], off offset:576
	global_load_dwordx4 v[198:201], v[208:209], off
	global_load_dwordx4 v[210:213], v[208:209], off offset:64
	global_load_dwordx4 v[218:221], v[208:209], off offset:512
	global_load_dwordx4 v[222:225], v[208:209], off offset:576
	v_or_b32_e32 v178, 48, v178
	v_ashrrev_i32_e32 v179, 31, v178
	v_lshlrev_b64 v[178:179], 12, v[178:179]
	v_lshl_add_u64 v[178:179], v[194:195], 0, v[178:179]
	global_load_dwordx4 v[226:229], v[178:179], off
	global_load_dwordx4 v[230:233], v[178:179], off offset:64
	global_load_dwordx4 v[234:237], v[178:179], off offset:512
	global_load_dwordx4 v[238:241], v[178:179], off offset:576
	s_waitcnt vmcnt(15)
	v_pk_fma_f32 v[130:131], v[126:127], v[152:153], v[130:131]
	v_pk_fma_f32 v[128:129], v[124:125], v[154:155], v[128:129]
	global_store_dwordx4 v[168:169], v[128:131], off
	s_waitcnt vmcnt(15)
	s_nop 0
	v_pk_fma_f32 v[130:131], v[122:123], v[156:157], v[134:135]
	v_pk_fma_f32 v[128:129], v[120:121], v[158:159], v[132:133]
	global_store_dwordx4 v[168:169], v[128:131], off offset:64
	s_waitcnt vmcnt(15)
	s_nop 0
	v_pk_fma_f32 v[130:131], v[106:107], v[160:161], v[138:139]
	v_pk_fma_f32 v[128:129], v[104:105], v[162:163], v[136:137]
	global_store_dwordx4 v[168:169], v[128:131], off offset:512
	s_waitcnt vmcnt(15)
	s_nop 0
	v_pk_fma_f32 v[130:131], v[98:99], v[164:165], v[142:143]
	v_pk_fma_f32 v[128:129], v[96:97], v[166:167], v[140:141]
	global_store_dwordx4 v[168:169], v[128:131], off offset:576
	s_waitcnt vmcnt(15)
	s_nop 0
	v_pk_fma_f32 v[130:131], v[118:119], v[152:153], v[172:173]
	v_pk_fma_f32 v[128:129], v[116:117], v[154:155], v[170:171]
	global_store_dwordx4 v[204:205], v[128:131], off
	v_lshl_add_u64 v[172:173], v[168:169], 0, s[96:97]
	v_lshl_add_u64 v[170:171], v[168:169], 0, s[2:3]
	s_waitcnt vmcnt(15)
	v_pk_fma_f32 v[130:131], v[114:115], v[156:157], v[176:177]
	v_pk_fma_f32 v[128:129], v[112:113], v[158:159], v[174:175]
	global_store_dwordx4 v[204:205], v[128:131], off offset:64
	v_add_co_u32_e32 v174, vcc, s76, v168
	s_waitcnt vmcnt(15)
	v_pk_fma_f32 v[130:131], v[90:91], v[160:161], v[186:187]
	v_pk_fma_f32 v[128:129], v[88:89], v[162:163], v[184:185]
	global_store_dwordx4 v[204:205], v[128:131], off offset:512
	v_addc_co_u32_e32 v175, vcc, 0, v169, vcc
	s_waitcnt vmcnt(15)
	v_pk_fma_f32 v[130:131], v[82:83], v[164:165], v[190:191]
	v_pk_fma_f32 v[128:129], v[80:81], v[166:167], v[188:189]
	global_store_dwordx4 v[204:205], v[128:131], off offset:576
	v_add_co_u32_e32 v176, vcc, s77, v168
	s_waitcnt vmcnt(15)
	v_pk_fma_f32 v[130:131], v[110:111], v[152:153], v[200:201]
	v_pk_fma_f32 v[128:129], v[108:109], v[154:155], v[198:199]
	global_store_dwordx4 v[208:209], v[128:131], off
	v_addc_co_u32_e32 v177, vcc, 0, v169, vcc
	s_waitcnt vmcnt(15)
	v_pk_fma_f32 v[130:131], v[102:103], v[156:157], v[212:213]
	v_pk_fma_f32 v[128:129], v[100:101], v[158:159], v[210:211]
	global_store_dwordx4 v[208:209], v[128:131], off offset:64
	s_mov_b64 s[2:3], 0xa0000
	v_lshl_add_u64 v[194:195], v[168:169], 0, s[2:3]
	s_waitcnt vmcnt(15)
	v_pk_fma_f32 v[130:131], v[78:79], v[160:161], v[220:221]
	v_pk_fma_f32 v[128:129], v[76:77], v[162:163], v[218:219]
	global_store_dwordx4 v[208:209], v[128:131], off offset:512
	s_mov_b32 s2, 0xa0000
	v_add_co_u32_e32 v204, vcc, s2, v168
	s_waitcnt vmcnt(15)
;     __device__ __forceinline__ void operator()(const f32x4 (&acc)[2][2][4][2], const Unit& u, int wr, int wc, int fr, int fq) const {
;     ...
;         for (int ai = 0; ai < 2; ++ai) {
;             f32x4 b[4][2][2];
; #pragma unroll
;             for (int m = 0; m < 4; ++m) { const size_t off = (size_t)(rowt + ai * HALF + m * 16) * D_MODEL + col0;
; #pragma unroll
;                 for (int bj = 0; bj < 2; ++bj)
; #pragma unroll
;                     for (int n = 0; n < 2; ++n) b[m][bj][n] = *(const f32x4*)(bp + off + bj * HALF + n * 16); }
; #pragma unroll
;             for (int m = 0; m < 4; ++m) { const size_t off = (size_t)(rowt + ai * HALF + m * 16) * D_MODEL + col0;
; #pragma unroll
;                 for (int bj = 0; bj < 2; ++bj)
; #pragma unroll
;                     for (int n = 0; n < 2; ++n) *(f32x4*)(op + off + bj * HALF + n * 16) = b[m][bj][n] + gv[bj][n] * acc[ai][bj][m][n]; }
	v_pk_fma_f32 v[130:131], v[74:75], v[164:165], v[224:225]
	v_pk_fma_f32 v[128:129], v[72:73], v[166:167], v[222:223]
	global_store_dwordx4 v[208:209], v[128:131], off offset:576
	v_addc_co_u32_e32 v205, vcc, 0, v169, vcc
	s_waitcnt vmcnt(15)
	v_pk_fma_f32 v[130:131], v[94:95], v[152:153], v[228:229]
	v_pk_fma_f32 v[128:129], v[92:93], v[154:155], v[226:227]
	global_store_dwordx4 v[178:179], v[128:131], off
	s_mov_b64 s[2:3], 0xb0000
	s_waitcnt vmcnt(15)
	v_pk_fma_f32 v[130:131], v[86:87], v[156:157], v[232:233]
	v_pk_fma_f32 v[128:129], v[84:85], v[158:159], v[230:231]
	global_store_dwordx4 v[178:179], v[128:131], off offset:64
	s_waitcnt vmcnt(15)
	s_nop 0
	v_pk_fma_f32 v[130:131], v[70:71], v[160:161], v[236:237]
	v_pk_fma_f32 v[128:129], v[68:69], v[162:163], v[234:235]
	global_store_dwordx4 v[178:179], v[128:131], off offset:512
	s_waitcnt vmcnt(15)
	s_nop 0
	v_pk_fma_f32 v[130:131], v[66:67], v[164:165], v[240:241]
	v_pk_fma_f32 v[128:129], v[64:65], v[166:167], v[238:239]
	global_store_dwordx4 v[178:179], v[128:131], off offset:576
	global_load_dwordx4 v[140:143], v[174:175], off
	global_load_dwordx4 v[136:139], v[172:173], off offset:64
	global_load_dwordx4 v[132:135], v[172:173], off offset:512
	s_nop 0
	global_load_dwordx4 v[128:131], v[172:173], off offset:576
	global_load_dwordx4 v[184:187], v[176:177], off
	global_load_dwordx4 v[188:191], v[170:171], off offset:64
	global_load_dwordx4 v[198:201], v[170:171], off offset:512
	global_load_dwordx4 v[210:213], v[170:171], off offset:576
	global_load_dwordx4 v[218:221], v[204:205], off
	global_load_dwordx4 v[222:225], v[194:195], off offset:64
	global_load_dwordx4 v[226:229], v[194:195], off offset:512
	global_load_dwordx4 v[230:233], v[194:195], off offset:576
	v_lshl_add_u64 v[178:179], v[168:169], 0, s[2:3]
	s_mov_b32 s2, 0xb0000
	v_add_co_u32_e32 v168, vcc, s2, v168
	s_nop 1
	v_addc_co_u32_e32 v169, vcc, 0, v169, vcc
	global_load_dwordx4 v[234:237], v[168:169], off
	global_load_dwordx4 v[238:241], v[178:179], off offset:64
	global_load_dwordx4 v[242:245], v[178:179], off offset:512
	global_load_dwordx4 v[246:249], v[178:179], off offset:576
	s_waitcnt vmcnt(15)
	v_pk_fma_f32 v[142:143], v[62:63], v[152:153], v[142:143]
	v_pk_fma_f32 v[140:141], v[60:61], v[154:155], v[140:141]
	s_waitcnt vmcnt(14)
	v_pk_fma_f32 v[138:139], v[58:59], v[156:157], v[138:139]
	s_waitcnt vmcnt(12)
	v_pk_fma_f32 v[130:131], v[38:39], v[164:165], v[130:131]
	v_pk_fma_f32 v[128:129], v[36:37], v[166:167], v[128:129]
	global_store_dwordx4 v[172:173], v[128:131], off offset:576
	v_pk_fma_f32 v[136:137], v[56:57], v[158:159], v[136:137]
	v_pk_fma_f32 v[134:135], v[46:47], v[160:161], v[134:135]
	s_waitcnt vmcnt(12)
	v_pk_fma_f32 v[130:131], v[54:55], v[152:153], v[186:187]
	v_pk_fma_f32 v[128:129], v[52:53], v[154:155], v[184:185]
	global_store_dwordx4 v[176:177], v[128:131], off
	v_pk_fma_f32 v[132:133], v[44:45], v[162:163], v[132:133]
	global_store_dwordx4 v[174:175], v[140:143], off
	s_waitcnt vmcnt(13)
	v_pk_fma_f32 v[130:131], v[50:51], v[156:157], v[190:191]
	v_pk_fma_f32 v[128:129], v[48:49], v[158:159], v[188:189]
	global_store_dwordx4 v[170:171], v[128:131], off offset:64
	global_store_dwordx4 v[172:173], v[136:139], off offset:64
	global_store_dwordx4 v[172:173], v[132:135], off offset:512
	s_waitcnt vmcnt(15)
	v_pk_fma_f32 v[130:131], v[30:31], v[160:161], v[200:201]
	v_pk_fma_f32 v[128:129], v[28:29], v[162:163], v[198:199]
	global_store_dwordx4 v[170:171], v[128:131], off offset:512
	s_waitcnt vmcnt(15)
	s_nop 0
	v_pk_fma_f32 v[130:131], v[22:23], v[164:165], v[212:213]
	v_pk_fma_f32 v[128:129], v[20:21], v[166:167], v[210:211]
	global_store_dwordx4 v[170:171], v[128:131], off offset:576
	s_waitcnt vmcnt(15)
	s_nop 0
	v_pk_fma_f32 v[130:131], v[42:43], v[152:153], v[220:221]
	v_pk_fma_f32 v[128:129], v[40:41], v[154:155], v[218:219]
	global_store_dwordx4 v[204:205], v[128:131], off
	s_waitcnt vmcnt(15)
	s_nop 0
	v_pk_fma_f32 v[130:131], v[34:35], v[156:157], v[224:225]
	v_pk_fma_f32 v[128:129], v[32:33], v[158:159], v[222:223]
	global_store_dwordx4 v[194:195], v[128:131], off offset:64
	s_waitcnt vmcnt(15)
	s_nop 0
	v_pk_fma_f32 v[130:131], v[14:15], v[160:161], v[228:229]
	v_pk_fma_f32 v[128:129], v[12:13], v[162:163], v[226:227]
	global_store_dwordx4 v[194:195], v[128:131], off offset:512
	s_waitcnt vmcnt(15)
	s_nop 0
	v_pk_fma_f32 v[130:131], v[10:11], v[164:165], v[232:233]
	v_pk_fma_f32 v[128:129], v[8:9], v[166:167], v[230:231]
	global_store_dwordx4 v[194:195], v[128:131], off offset:576
	s_waitcnt vmcnt(15)
	s_nop 0
	v_pk_fma_f32 v[130:131], v[26:27], v[152:153], v[236:237]
	v_pk_fma_f32 v[128:129], v[24:25], v[154:155], v[234:235]
	global_store_dwordx4 v[168:169], v[128:131], off
	s_waitcnt vmcnt(15)
	s_nop 0
	v_pk_fma_f32 v[130:131], v[18:19], v[156:157], v[240:241]
	v_pk_fma_f32 v[128:129], v[16:17], v[158:159], v[238:239]
	global_store_dwordx4 v[178:179], v[128:131], off offset:64
	s_waitcnt vmcnt(15)
	s_nop 0
	v_pk_fma_f32 v[130:131], v[6:7], v[160:161], v[244:245]
	v_pk_fma_f32 v[128:129], v[4:5], v[162:163], v[242:243]
	global_store_dwordx4 v[178:179], v[128:131], off offset:512
	s_waitcnt vmcnt(15)
	s_nop 0
	v_pk_fma_f32 v[130:131], v[2:3], v[164:165], v[248:249]
	v_pk_fma_f32 v[128:129], v[0:1], v[166:167], v[246:247]
	global_store_dwordx4 v[178:179], v[128:131], off offset:576
	s_branch .LBB0_970
